# NSA compressed-branch K/V staging: all 16 loads issued before the entry barrier, counted waits (was 4 dependent round trips)
# baseline (speedup 1.0000x reference)
.LBB0_303:
	s_and_b64 vcc, exec, s[40:41]
	s_cbranch_vccz .LBB0_298
	s_sub_i32 s45, s21, 0x100
	s_lshr_b32 s45, s45, 3
	s_sub_i32 s45, 63, s45
	s_lshl_b32 s45, s45, 3
	s_and_b32 s46, s21, 7
	s_or_b32 s45, s45, s46
	s_cmpk_lt_i32 s21, 0x100
	s_cselect_b32 s44, s21, s45
	v_mov_b32_e32 v118, v131
	s_lshl_b32 s22, s44, 2
	s_load_dwordx2 s[40:41], s[12:13], 0x170
	s_andn2_b32 s22, s22, 31
	v_ashrrev_i32_e32 v120, 3, v118
	s_sub_i32 s23, 0x7e0, s22
	v_and_b32_e32 v126, -8, v120
	v_bfe_u32 v121, v118, 2, 3
	v_add_u32_e32 v0, s23, v126
	s_lshl_b32 s24, s44, 10
	s_and_b32 s79, s44, 1
	v_and_b32_e32 v127, 3, v118
	v_or_b32_e32 v117, v0, v121
	s_and_b32 s24, s24, 0x1800
	v_lshl_or_b32 v129, s79, 2, v127
	v_add_u32_e32 v114, s24, v117
	s_waitcnt lgkmcnt(0)
	v_mov_b64_e32 v[2:3], s[40:41]
	v_bfe_u32 v135, v118, 5, 1
	v_mad_i64_i32 v[124:125], s[40:41], v114, s33, v[2:3]
	v_lshlrev_b32_e32 v0, 8, v129
	v_lshl_add_u64 v[2:3], v[124:125], 0, v[0:1]
	v_lshlrev_b32_e32 v122, 4, v135
	v_mov_b32_e32 v123, v1
	v_lshl_add_u64 v[2:3], v[2:3], 0, v[122:123]
	s_load_dwordx4 s[28:31], s[12:13], 0x198
	global_load_dwordx4 v[82:85], v[2:3], off
	global_load_dwordx4 v[86:89], v[2:3], off offset:32
	global_load_dwordx4 v[90:93], v[2:3], off offset:64
	global_load_dwordx4 v[94:97], v[2:3], off offset:96
	global_load_dwordx4 v[98:101], v[2:3], off offset:128
	global_load_dwordx4 v[102:105], v[2:3], off offset:160
	global_load_dwordx4 v[106:109], v[2:3], off offset:192
	global_load_dwordx4 v[110:113], v[2:3], off offset:224
	s_lshl_b32 s25, s44, 7
	s_and_b32 s82, s25, 0x380
	v_add_u32_e32 v0, 1, v129
	s_lshl_b32 s25, s82, 8
	v_cvt_f32_ubyte0_e32 v0, v0
	s_waitcnt lgkmcnt(0)
	s_add_u32 s28, s28, s25
	v_exp_f32_e64 v5, -v0
	s_addc_u32 s29, s29, 0
	s_add_u32 s30, s30, s25
	v_lshlrev_b32_e32 v0, 4, v118
	s_addc_u32 s31, s31, 0
	v_and_b32_e32 v0, 0xf0, v0
	v_and_b32_e32 v173, 31, v118
	v_ashrrev_i32_e32 v115, 31, v114
	v_lshlrev_b32_e32 v116, 7, v129
	v_lshlrev_b32_e32 v18, 3, v135
	v_lshlrev_b32_e32 v171, 3, v118
	v_lshl_add_u64 v[2:3], s[28:29], 0, v[0:1]
	v_add_u32_e32 v4, 16, v0
	v_lshl_add_u64 v[6:7], s[30:31], 0, v[0:1]
	s_mov_b32 s25, 0
	v_lshlrev_b32_e32 v8, 4, v118
	v_add_u32_e32 v8, 0x1000, v8
	v_add_u32_e32 v9, 0x2000, v8
	v_add_u32_e32 v10, 0x4000, v8
	v_add_u32_e32 v11, 0x6000, v8
	global_load_dwordx4 v[20:23], v8, s[28:29] offset:-4096
	global_load_dwordx4 v[24:27], v8, s[28:29]
	global_load_dwordx4 v[28:31], v9, s[28:29] offset:-4096
	global_load_dwordx4 v[32:35], v9, s[28:29]
	global_load_dwordx4 v[36:39], v10, s[28:29] offset:-4096
	global_load_dwordx4 v[40:43], v10, s[28:29]
	global_load_dwordx4 v[44:47], v11, s[28:29] offset:-4096
	global_load_dwordx4 v[48:51], v11, s[28:29]
	global_load_dwordx4 v[52:55], v8, s[30:31] offset:-4096
	global_load_dwordx4 v[56:59], v8, s[30:31]
	global_load_dwordx4 v[60:63], v9, s[30:31] offset:-4096
	global_load_dwordx4 v[64:67], v9, s[30:31]
	global_load_dwordx4 v[68:71], v10, s[30:31] offset:-4096
	global_load_dwordx4 v[72:75], v10, s[30:31]
	global_load_dwordx4 v[76:79], v11, s[30:31] offset:-4096
	global_load_dwordx4 v[12:15], v11, s[30:31]
	s_barrier
	v_lshrrev_b32_e32 v17, 4, v118
	v_mad_u32_u24 v16, v17, s36, v4
	s_waitcnt vmcnt(15)
	ds_write_b128 v16, v[20:23]
	s_waitcnt vmcnt(14)
	ds_write_b128 v16, v[24:27] offset:4352
	s_waitcnt vmcnt(13)
	ds_write_b128 v16, v[28:31] offset:8704
	s_waitcnt vmcnt(12)
	ds_write_b128 v16, v[32:35] offset:13056
	s_waitcnt vmcnt(11)
	ds_write_b128 v16, v[36:39] offset:17408
	s_waitcnt vmcnt(10)
	ds_write_b128 v16, v[40:43] offset:21760
	s_waitcnt vmcnt(9)
	ds_write_b128 v16, v[44:47] offset:26112
	s_waitcnt vmcnt(8)
	ds_write_b128 v16, v[48:51] offset:30464
	s_waitcnt vmcnt(7)
	ds_write_b128 v16, v[52:55] offset:34816
	s_waitcnt vmcnt(6)
	ds_write_b128 v16, v[56:59] offset:39168
	s_waitcnt vmcnt(5)
	ds_write_b128 v16, v[60:63] offset:43520
	s_waitcnt vmcnt(4)
	ds_write_b128 v16, v[64:67] offset:47872
	s_waitcnt vmcnt(3)
	ds_write_b128 v16, v[68:71] offset:52224
	s_waitcnt vmcnt(2)
	ds_write_b128 v16, v[72:75] offset:56576
	s_waitcnt vmcnt(1)
	ds_write_b128 v16, v[76:79] offset:60928
	s_waitcnt vmcnt(0)
	ds_write_b128 v16, v[12:15] offset:65280
	v_cmp_gt_i32_e32 vcc, 32, v118
	s_and_saveexec_b64 s[40:41], vcc
	v_lshl_add_u32 v0, v118, 2, 16
	v_add_u32_e32 v0, 0x11f80, v0
	ds_write_b32 v0, v1
	s_or_b64 exec, exec, s[40:41]
	v_and_b32_e32 v3, 64, v160
	v_xor_b32_e32 v2, 32, v160
	v_add_u32_e32 v128, 64, v3
	v_cmp_lt_i32_e32 vcc, v2, v128
	s_lshl_b32 s28, s44, 2
	s_and_b32 s28, s28, 0xffffffe0
	v_lshlrev_b32_e32 v0, 6, v135
	v_cndmask_b32_e32 v2, v160, v2, vcc
	v_lshlrev_b32_e32 v172, 2, v2
	v_add_u32_e32 v2, v121, v126
	v_subrev_u32_e32 v2, s28, v2
	v_sub_u32_e32 v2, v2, v0
	v_add_u32_e32 v19, 0x7e0, v2
	v_mul_u32_u24_e32 v2, 0x110, v173
	v_mul_f32_e32 v119, 0x3fb8aa3b, v5
	s_mov_b32 s25, 0
	v_add3_u32 v20, v2, v122, 16
	v_mov_b32_e32 v139, 0xf149f2ca
	v_mov_b32_e32 v22, 0
	s_movk_i32 s28, 0x9e
	s_movk_i32 s29, 0xae
	s_movk_i32 s30, 0xbe
	s_movk_i32 s31, 0xce
	s_movk_i32 s34, 0x11e
	s_movk_i32 s94, 0x12e
	s_movk_i32 s95, 0x13e
	s_movk_i32 s73, 0x14e
	s_movk_i32 s89, 0x1ae
	s_movk_i32 s1, 0x1be
	s_waitcnt lgkmcnt(0)
	s_barrier
